# P2b gate-logit projection on f32 MFMA (v_mfma_f32_32x32x2_f32, f32 accumulate) instead of scalar FMAs + broadcast LDS reads; S2 lane mapping permuted
# speedup vs baseline: 1.0081x; 1.0081x over previous
; #define LAS __attribute__((address_space(3)))
; #define LBAR() do { asm volatile("s_waitcnt lgkmcnt(0)" ::: "memory"); __builtin_amdgcn_s_barrier(); asm volatile("" ::: "memory"); } while (0)
; __device__ __forceinline__ void gla_prep_phase(LAS unsigned char* lds, const GlaPrepArgs& A, int bid, int G) {
;     ...
;     int unit = bid;
;     if (unit < nunits) GLA_PREFETCH(unit);
;   for (; unit < nunits; unit += G) {
;     const int h = (unit / NCH) % 4;
;     unsigned char* blob = A.blobA + (size_t)unit * BLOBA; unsigned char* blobB = A.blobB + (size_t)unit * BLOBB;
;     *(LAS f32x4*)(lds + L_R + (tid >> 3) * 128 + (tid & 7) * 16) = pr;
; #pragma unroll
;     for (int i = 0; i < 4; ++i) { const int id = i * 512 + tid; *(LAS v4u*)(lds + L_V + (id >> 5) * VS_ + (id & 31) * 16) = pv[i]; }
; #pragma unroll
;     for (int i = 0; i < 2; ++i) { const int id = i * 512 + tid; *(LAS v4u*)(lds + L_QGF + (id >> 4) * QS_ + (id & 15) * 16) = pq[i]; *(LAS v4u*)(lds + L_KGF + (id >> 4) * QS_ + (id & 15) * 16) = pk[i]; }
;     LBAR();
;     {
;         const int dd = tid & 127, pg = tid >> 7, d = h * 128 + dd;
.LBB0_418:
	s_andn2_b64 vcc, exec, s[2:3]
	s_cbranch_vccnz .LBB0_489
	v_readlane_b32 s2, v251, 43
	v_writelane_b32 v254, s42, 55
	v_mov_b32_e32 v70, v0
	v_readlane_b32 s3, v251, 44
	v_writelane_b32 v254, s43, 56
	s_andn2_b64 vcc, exec, s[2:3]
	v_readfirstlane_b32 s3, v70
	s_cbranch_vccnz .LBB0_434
	v_ashrrev_i32_e32 v72, 3, v70
	v_readlane_b32 s4, v251, 45
	v_ashrrev_i32_e32 v73, 31, v72
	v_readlane_b32 s5, v251, 46
	v_readlane_b32 s76, v251, 25
	v_readlane_b32 s77, v251, 26
	s_waitcnt vmcnt(0)
	v_lshl_add_u64 v[4:5], s[4:5], 0, v[72:73]
	v_lshlrev_b64 v[4:5], 8, v[4:5]
	v_lshlrev_b32_e32 v3, 4, v70
	v_lshl_add_u64 v[4:5], s[76:77], 0, v[4:5]
	v_and_b32_e32 v130, 0x70, v3
	v_ashrrev_i32_e32 v74, 5, v70
	v_lshl_add_u64 v[4:5], v[4:5], 0, v[130:131]
	v_readlane_b32 s6, v251, 49
	v_ashrrev_i32_e32 v75, 31, v74
	global_load_dwordx4 v[34:37], v[4:5], off offset:128
	v_and_b32_e32 v4, 0x1f0, v3
	v_mov_b32_e32 v5, v131
	v_readlane_b32 s7, v251, 50
	v_lshl_add_u64 v[8:9], s[4:5], 0, v[74:75]
	v_add_u32_e32 v12, 0x200, v70
	v_lshl_add_u64 v[6:7], s[6:7], 0, v[4:5]
	v_lshlrev_b64 v[8:9], 11, v[8:9]
	v_ashrrev_i32_e32 v76, 5, v12
	v_lshl_add_u64 v[8:9], v[6:7], 0, v[8:9]
	v_ashrrev_i32_e32 v77, 31, v76
	global_load_dwordx4 v[38:41], v[8:9], off
	v_lshl_add_u64 v[8:9], s[4:5], 0, v[76:77]
	v_lshlrev_b64 v[8:9], 11, v[8:9]
	v_lshl_add_u64 v[8:9], v[6:7], 0, v[8:9]
	global_load_dwordx4 v[42:45], v[8:9], off
	v_add_u32_e32 v8, 0x400, v70
	v_ashrrev_i32_e32 v78, 5, v8
	v_ashrrev_i32_e32 v79, 31, v78
	v_lshl_add_u64 v[8:9], s[4:5], 0, v[78:79]
	v_lshlrev_b64 v[8:9], 11, v[8:9]
	v_lshl_add_u64 v[8:9], v[6:7], 0, v[8:9]
	global_load_dwordx4 v[46:49], v[8:9], off
	v_add_u32_e32 v8, 0x600, v70
	v_ashrrev_i32_e32 v80, 5, v8
	v_ashrrev_i32_e32 v81, 31, v80
	v_lshl_add_u64 v[8:9], s[4:5], 0, v[80:81]
	v_lshlrev_b64 v[8:9], 11, v[8:9]
	v_ashrrev_i32_e32 v82, 4, v70
	v_lshl_add_u64 v[6:7], v[6:7], 0, v[8:9]
	v_readlane_b32 s6, v251, 53
	v_ashrrev_i32_e32 v83, 31, v82
	global_load_dwordx4 v[50:53], v[6:7], off
	v_and_b32_e32 v6, 0xf0, v3
	v_mov_b32_e32 v7, v131
	v_readlane_b32 s7, v251, 54
	v_lshl_add_u64 v[10:11], s[4:5], 0, v[82:83]
	v_lshlrev_b64 v[10:11], 11, v[10:11]
	v_lshl_add_u64 v[8:9], s[6:7], 0, v[6:7]
	v_ashrrev_i32_e32 v84, 4, v12
	v_lshl_add_u64 v[10:11], v[8:9], 0, v[10:11]
	v_ashrrev_i32_e32 v85, 31, v84
	global_load_dwordx4 v[54:57], v[10:11], off
	global_load_dwordx4 v[58:61], v[10:11], off offset:1024
	v_lshl_add_u64 v[10:11], s[4:5], 0, v[84:85]
	v_lshlrev_b64 v[10:11], 11, v[10:11]
	v_lshl_add_u64 v[8:9], v[8:9], 0, v[10:11]
	global_load_dwordx4 v[62:65], v[8:9], off
	global_load_dwordx4 v[66:69], v[8:9], off offset:1024
	s_ashr_i32 s2, s3, 6
	s_cmp_gt_i32 s2, 3
	v_lshrrev_b32_e32 v12, 2, v70
	v_and_b32_e32 v180, 0x11f, v70
	v_and_b32_e32 v181, 0xc0, v70
	v_lshrrev_b32_e32 v181, 1, v181
	v_or_b32_e32 v180, v180, v181
	v_and_b32_e32 v181, 32, v70
	v_lshl_or_b32 v180, v181, 2, v180
	s_nop 0
	v_and_b32_e32 v86, 0x7f, v180
	v_readlane_b32 s4, v254, 2
	s_cselect_b64 s[70:71], -1, 0
	s_lshl_b32 s5, s2, 4
	v_and_b32_e32 v12, 8, v12
	v_lshl_add_u32 v98, v180, 2, s4
	v_lshl_add_u32 v99, v86, 2, s4
	s_movk_i32 s4, 0x80
	v_and_or_b32 v13, s5, 48, v12
	v_readlane_b32 s5, v254, 3
	v_cmp_gt_u32_e64 s[36:37], s4, v180
	s_add_i32 s4, s2, -4
	v_mov_b32_e32 v14, s5
	s_ashr_i32 s5, s3, 7
	s_and_b32 s6, s2, 1
	s_cmp_ge_i32 s5, s6
	s_cselect_b64 s[38:39], -1, 0
	s_lshl_b32 s7, s5, 5
	v_readlane_b32 s34, v254, 1
	v_writelane_b32 v254, s38, 53
	s_cmp_le_i32 s5, s6
	v_lshlrev_b32_e32 v20, 1, v70
	v_writelane_b32 v254, s39, 54
	s_cselect_b64 s[38:39], -1, 0
	s_andn2_b32 s3, s3, 63
	v_and_b32_e32 v20, 62, v20
	s_add_i32 s3, s34, s3
	v_add_u32_e32 v20, s3, v20
	s_ashr_i32 s3, s2, 31
	s_lshl_b64 s[74:75], s[2:3], 12
	s_movk_i32 s3, 0x210
	v_ashrrev_i32_e32 v10, 7, v180
	v_writelane_b32 v254, s38, 57
	v_mul_lo_u32 v22, v74, s3
	v_mul_lo_u32 v23, v76, s3
	v_mul_lo_u32 v24, v78, s3
	v_mul_lo_u32 v25, v80, s3
	s_movk_i32 s3, 0x1100
	v_and_b32_e32 v181, 3, v70
	v_bfe_u32 v182, v70, 3, 2
	v_lshl_or_b32 v181, v182, 2, v181
	v_bfe_u32 v182, v70, 2, 1
	v_lshl_or_b32 v181, v182, 4, v181
	v_bfe_u32 v182, v70, 8, 1
	v_lshl_or_b32 v181, v182, 5, v181
	v_bfe_u32 v182, v70, 5, 1
	v_lshlrev_b32_e32 v182, 5, v182
	v_lshl_or_b32 v87, v181, 7, v182
	v_and_b32_e32 v11, 0x3fffff80, v180
	v_writelane_b32 v254, s39, 58
	v_cmp_lt_i32_e64 s[38:39], 0, v10
	v_cmp_gt_i32_e64 s[40:41], 0, v10
	v_cmp_lt_i32_e64 s[42:43], 1, v10
	v_cmp_gt_i32_e64 s[44:45], 1, v10
	v_cmp_lt_i32_e64 s[46:47], 2, v10
	v_cmp_gt_i32_e64 s[48:49], 2, v10
	v_cmp_lt_i32_e64 s[50:51], 3, v10
	v_cmp_gt_i32_e64 s[52:53], 3, v10
	v_mul_lo_u32 v10, v10, s3
	s_lshl_b32 s3, s4, 2
	v_lshl_add_u32 v100, v11, 2, v99
	v_and_b32_e32 v11, 31, v70
	s_and_b32 s3, s3, 0xfffffe0
	v_or_b32_e32 v28, s3, v11
	s_lshl_b32 s3, s4, 5
	s_movk_i32 s54, 0x110
	s_and_b32 s3, s3, 0xe0
	v_mul_lo_u32 v28, v28, s54
	s_add_i32 s3, s3, 0
	v_add_u32_e32 v28, s3, v28
	s_lshl_b32 s3, s2, 2
	s_and_b32 s3, s3, 0xfffffe0
	v_or_b32_e32 v29, s3, v11
	s_lshl_b32 s3, s2, 5
	s_and_b32 s3, s3, 0xe0
	v_readlane_b32 s5, v254, 4
	v_lshrrev_b32_e32 v21, 1, v70
	v_mul_lo_u32 v29, v29, s54
	s_add_i32 s3, s3, 0
	v_lshl_or_b32 v16, s6, 5, v11
	v_mov_b32_e32 v18, s5
	v_readlane_b32 s5, v254, 5
	v_and_b32_e32 v21, 16, v21
	v_add_u32_e32 v29, s3, v29
	s_add_i32 s3, s2, 4
	v_lshl_add_u32 v19, v16, 1, s5
	v_add_u32_e32 v21, s5, v21
; __device__ __forceinline__ void gla_prep_phase(LAS unsigned char* lds, const GlaPrepArgs& A, int bid, int G) {
;     ...
;         const int dd = tid & 127, pg = tid >> 7, d = h * 128 + dd;
;         float wf[16], wb[16];
; #pragma unroll
;         for (int i = 0; i < 16; ++i) { wf[i] = A.w2f[i * 512 + d]; wb[i] = A.w2b[i * 512 + d]; }
;         const float bf_ = A.b2f[d], bb_ = A.b2b[d];
;         float lf[16], lb[16];
; #pragma unroll
;         for (int pp = 0; pp < 16; ++pp) {
;             const LAS float* rr = (const LAS float*)(lds + L_R) + (pg * 16 + pp) * 32;
;             float xf = bf_, xb = bb_;
; #pragma unroll
;             for (int i4 = 0; i4 < 4; ++i4) { const f32x4 a = *(const LAS f32x4*)(rr + 4 * i4), b = *(const LAS f32x4*)(rr + 16 + 4 * i4);
;                 xf += a.x * wf[4 * i4] + a.y * wf[4 * i4 + 1] + a.z * wf[4 * i4 + 2] + a.w * wf[4 * i4 + 3];
;                 xb += b.x * wb[4 * i4] + b.y * wb[4 * i4 + 1] + b.z * wb[4 * i4 + 2] + b.w * wb[4 * i4 + 3]; }
;             lf[pp] = logsig2(xf) * (1.f / 16.f); lb[pp] = logsig2(xb) * (1.f / 16.f);
;         }
; #pragma unroll
;         for (int pp = 1; pp < 16; ++pp) lf[pp] += lf[pp - 1];
; #pragma unroll
;     ...
;         LAS float* tot = (LAS float*)(lds + L_TOT);
;         tot[pg * 128 + dd] = lf[15]; tot[512 + pg * 128 + dd] = lb[0];
;         LBAR();
;         float offf = 0.f, offb = 0.f, glf = 0.f, glb = 0.f;
; #pragma unroll
;         for (int g = 0; g < 4; ++g) { const float tf = tot[g * 128 + dd], tb = tot[512 + g * 128 + dd]; glf += tf; glb += tb; if (g < pg) offf += tf; if (g > pg) offb += tb; }
;         const float eglf = __builtin_amdgcn_exp2f(glf), eglb = __builtin_amdgcn_exp2f(glb);
;         if (pg == 0) { float* sc = (float*)(blob + B_SC); sc[dd] = eglf; sc[128 + dd] = eglb; }
; #pragma unroll
;         for (int pp = 0; pp < 16; ++pp) {
;             const int o = (pg * 16 + pp) * QS_ + dd * 2;
;             const float qv = bf2f(*(const LAS unsigned short*)(lds + L_QGF + o)) * QSCALE, kv = bf2f(*(const LAS unsigned short*)(lds + L_KGF + o));
;             const float ef = __builtin_amdgcn_exp2f(lf[pp] + offf), eb = __builtin_amdgcn_exp2f(lb[pp] + offb);
;             const float rf = __builtin_amdgcn_rcpf(ef), rb = __builtin_amdgcn_rcpf(eb);
;             *(LAS unsigned short*)(lds + L_QGF + o) = (unsigned short)(pkbf(qv * ef, 0.f) & 0xffffu);
	s_lshl_b32 s5, s3, 2
	s_and_b32 s5, s5, 0xfffffe0
	v_or_b32_e32 v30, s5, v11
	s_lshl_b32 s5, s3, 5
	s_and_b32 s5, s5, 0xe0
	v_add_u32_e32 v8, s34, v4
	s_lshl_b32 s34, s4, 10
	v_mul_lo_u32 v30, v30, s54
	s_add_i32 s5, s5, 0
	s_lshl_b32 s4, s4, 3
	s_lshl_b32 s72, s2, 12
	s_lshl_b32 s84, s2, 10
	v_add_u32_e32 v30, s5, v30
	s_add_i32 s5, s2, 8
	s_and_b32 s4, s4, 0x7fffffe0
	s_lshl_b32 s2, s2, 3
	v_or_b32_e32 v32, s4, v11
	s_and_b32 s2, s2, 0x7fffffe0
	v_lshlrev_b32_e32 v103, 1, v32
	v_or_b32_e32 v32, s2, v11
	s_lshl_b32 s2, s3, 3
	s_and_b32 s2, s2, 0x7fffffe0
	v_mad_u32_u24 v101, v13, s54, 0
	v_mad_u32_u24 v102, v13, s54, v14
	v_bfe_u32 v13, v70, 5, 1
	v_lshlrev_b32_e32 v104, 1, v32
	v_or_b32_e32 v32, s2, v11
	s_lshl_b32 s2, s5, 3
	v_lshlrev_b32_e32 v15, 4, v13
	s_and_b32 s2, s2, 0x7fffffe0
	v_lshl_or_b32 v13, v13, 2, s7
	s_lshl_b32 s85, s3, 10
	v_lshlrev_b32_e32 v105, 1, v32
	v_or_b32_e32 v32, s2, v11
	v_cmp_gt_i32_e64 s[2:3], v13, v16
	v_or_b32_e32 v33, 1, v13
	v_lshlrev_b32_e32 v106, 1, v32
	v_writelane_b32 v255, s2, 1
	s_lshl_b32 s6, s5, 2
	s_and_b32 s6, s6, 0xfffffe0
	v_writelane_b32 v255, s3, 2
	s_movk_i32 s2, 0x90
	v_mul_lo_u32 v32, v13, s2
	v_cmp_lt_i32_e64 s[2:3], v33, v16
	v_or_b32_e32 v33, 2, v13
	v_or_b32_e32 v31, s6, v11
	v_writelane_b32 v255, s2, 3
	s_lshl_b32 s6, s5, 5
	s_and_b32 s6, s6, 0xe0
	v_writelane_b32 v255, s3, 4
	v_cmp_lt_i32_e64 s[2:3], v33, v16
	v_mul_lo_u32 v31, v31, s54
	s_add_i32 s6, s6, 0
	v_writelane_b32 v255, s2, 5
	v_readlane_b32 s78, v251, 47
	v_or_b32_e32 v14, s7, v11
	v_writelane_b32 v255, s3, 6
	v_cmp_gt_i32_e64 s[2:3], v33, v16
	v_or_b32_e32 v33, 3, v13
	v_add_u32_e32 v31, s6, v31
	v_writelane_b32 v255, s2, 7
	s_lshl_b32 s86, s5, 10
	v_readlane_b32 s79, v251, 48
	v_writelane_b32 v255, s3, 8
	v_cmp_lt_i32_e64 s[2:3], v33, v16
	v_mul_lo_u32 v14, v14, s54
	v_mad_u32_u24 v17, v16, s54, 0
	v_writelane_b32 v255, s2, 9
	v_mad_u32_u24 v18, v16, s54, v18
	v_mul_lo_u32 v26, v82, s54
	v_writelane_b32 v255, s3, 10
	v_cmp_gt_i32_e64 s[2:3], v33, v16
	v_or_b32_e32 v33, 8, v13
	v_mul_lo_u32 v27, v84, s54
	v_writelane_b32 v255, s2, 11
	v_cmp_lt_i32_e64 s[54:55], v13, v16
	v_lshl_add_u64 v[90:91], s[78:79], 0, v[4:5]
	v_writelane_b32 v255, s3, 12
	v_cmp_lt_i32_e64 s[2:3], v33, v16
	v_readlane_b32 s78, v251, 51
	v_and_b32_e32 v2, 63, v70
	v_writelane_b32 v255, s2, 15
	v_lshl_add_u32 v3, v72, 7, 0
	v_add_u32_e32 v9, 0, v6
	v_writelane_b32 v255, s3, 16
	v_cmp_gt_i32_e64 s[2:3], v33, v16
	v_or_b32_e32 v33, 9, v13
	v_add_u32_e32 v14, 0, v14
	v_writelane_b32 v255, s2, 17
	v_lshl_or_b32 v10, v86, 1, v10
	v_mul_u32_u24_e32 v11, 0x90, v11
	v_writelane_b32 v255, s3, 18
	v_cmp_lt_i32_e64 s[2:3], v33, v16
	v_readlane_b32 s79, v251, 52
	v_readlane_b32 s67, v252, 54
	v_writelane_b32 v255, s2, 19
	v_mov_b32_e32 v71, v131
	v_lshlrev_b32_e32 v88, 4, v2
	v_writelane_b32 v255, s3, 20
	v_cmp_gt_i32_e64 s[2:3], v33, v16
	v_or_b32_e32 v33, 10, v13
	v_mov_b32_e32 v89, v131
	v_writelane_b32 v255, s2, 21
	s_ashr_i32 s73, s72, 31
	v_lshl_add_u64 v[92:93], s[78:79], 0, v[6:7]
	v_writelane_b32 v255, s3, 22
	v_cmp_lt_i32_e64 s[2:3], v33, v16
	v_lshl_add_u64 v[94:95], s[76:77], 0, v[130:131]
	s_lshl_b32 s67, s67, 6
	v_writelane_b32 v255, s2, 23
	s_lshl_b32 s87, s93, 6
	v_add_u32_e32 v107, v3, v130
	v_writelane_b32 v255, s3, 24
	v_cmp_gt_i32_e64 s[2:3], v33, v16
	v_or_b32_e32 v33, 11, v13
	v_add_u32_e32 v108, v8, v22
	v_writelane_b32 v255, s2, 25
	v_add_u32_e32 v109, v8, v23
	v_add_u32_e32 v110, v8, v24
	v_writelane_b32 v255, s3, 26
	v_cmp_lt_i32_e64 s[2:3], v33, v16
	v_add_u32_e32 v111, v8, v25
	v_add_u32_e32 v112, v9, v26
	v_writelane_b32 v255, s2, 27
	v_add_u32_e32 v113, v9, v27
	v_add_u32_e32 v114, 0, v10
	v_writelane_b32 v255, s3, 28
	v_cmp_gt_i32_e64 s[2:3], v33, v16
	v_or_b32_e32 v33, 16, v13
	v_add_u32_e32 v115, v28, v12
	v_writelane_b32 v255, s2, 29
	v_add_u32_e32 v116, v29, v12
	v_add_u32_e32 v117, v30, v12
	v_writelane_b32 v255, s3, 30
	v_cmp_lt_i32_e64 s[2:3], v33, v16
	v_add_u32_e32 v118, v31, v12
	v_add_u32_e32 v119, v17, v15
	v_writelane_b32 v255, s2, 31
	v_add_u32_e32 v120, v18, v15
	v_add_u32_e32 v121, v19, v32
	v_writelane_b32 v255, s3, 32
	v_cmp_gt_i32_e64 s[2:3], v33, v16
	v_or_b32_e32 v33, 17, v13
	v_add_u32_e32 v123, v21, v11
	v_writelane_b32 v255, s2, 33
	v_lshlrev_b32_e32 v130, 3, v2
	v_add_u32_e32 v124, v14, v15
	v_writelane_b32 v255, s3, 34
	v_cmp_lt_i32_e64 s[2:3], v33, v16
	v_readlane_b32 s76, v254, 16
	s_nop 0
	v_writelane_b32 v255, s2, 35
	s_nop 1
	v_writelane_b32 v255, s3, 36
	v_cmp_gt_i32_e64 s[2:3], v33, v16
	v_or_b32_e32 v33, 18, v13
	v_cmp_gt_i32_e64 s[94:95], v33, v16
	v_writelane_b32 v255, s2, 37
	s_nop 1
	v_writelane_b32 v255, s3, 38
	v_cmp_lt_i32_e64 s[2:3], v33, v16
	v_or_b32_e32 v33, 19, v13
	v_cmp_lt_i32_e64 s[68:69], v33, v16
	v_writelane_b32 v255, s2, 39
	s_nop 1
	v_writelane_b32 v255, s3, 40
	v_cmp_gt_i32_e64 s[2:3], v33, v16
	v_or_b32_e32 v33, 24, v13
	v_cmp_lt_i32_e64 s[4:5], v33, v16
	v_cmp_gt_i32_e64 s[6:7], v33, v16
	v_or_b32_e32 v33, 25, v13
	v_cmp_lt_i32_e64 s[60:61], v33, v16
	v_cmp_gt_i32_e64 s[62:63], v33, v16
	v_or_b32_e32 v33, 26, v13
	v_or_b32_e32 v13, 27, v13
	v_cmp_lt_i32_e64 s[56:57], v13, v16
	v_cmp_gt_i32_e64 s[58:59], v13, v16
	v_mul_u32_u24_e32 v13, 0x210, v12
	v_cmp_lt_i32_e64 s[64:65], v33, v16
	v_cmp_gt_i32_e64 s[82:83], v33, v16
	v_add_u32_e32 v122, v20, v13
	s_waitcnt vmcnt(0)
	s_nop 0
	s_branch .LBB0_423

; #define LAS __attribute__((address_space(3)))
; #define LBAR() do { asm volatile("s_waitcnt lgkmcnt(0)" ::: "memory"); __builtin_amdgcn_s_barrier(); asm volatile("" ::: "memory"); } while (0)
; __device__ __forceinline__ float logsig2(float x) { const float xc = fminf(fmaxf(x, -60.f), 60.f); return -__builtin_amdgcn_logf(1.0f + __builtin_amdgcn_exp2f(-1.4426950408889634f * xc)); }
; __device__ __forceinline__ void gla_prep_phase(LAS unsigned char* lds, const GlaPrepArgs& A, int bid, int G) {
;     ...
;     *(LAS f32x4*)(lds + L_R + (tid >> 3) * 128 + (tid & 7) * 16) = pr;
; #pragma unroll
;     for (int i = 0; i < 4; ++i) { const int id = i * 512 + tid; *(LAS v4u*)(lds + L_V + (id >> 5) * VS_ + (id & 31) * 16) = pv[i]; }
; #pragma unroll
;     for (int i = 0; i < 2; ++i) { const int id = i * 512 + tid; *(LAS v4u*)(lds + L_QGF + (id >> 4) * QS_ + (id & 15) * 16) = pq[i]; *(LAS v4u*)(lds + L_KGF + (id >> 4) * QS_ + (id & 15) * 16) = pk[i]; }
;     LBAR();
;     {
;         const int dd = tid & 127, pg = tid >> 7, d = h * 128 + dd;
;         float wf[16], wb[16];
; #pragma unroll
;         for (int i = 0; i < 16; ++i) { wf[i] = A.w2f[i * 512 + d]; wb[i] = A.w2b[i * 512 + d]; }
;         const float bf_ = A.b2f[d], bb_ = A.b2b[d];
;         float lf[16], lb[16];
; #pragma unroll
;         for (int pp = 0; pp < 16; ++pp) {
;             const LAS float* rr = (const LAS float*)(lds + L_R) + (pg * 16 + pp) * 32;
;             float xf = bf_, xb = bb_;
; #pragma unroll
;             for (int i4 = 0; i4 < 4; ++i4) { const f32x4 a = *(const LAS f32x4*)(rr + 4 * i4), b = *(const LAS f32x4*)(rr + 16 + 4 * i4);
;                 xf += a.x * wf[4 * i4] + a.y * wf[4 * i4 + 1] + a.z * wf[4 * i4 + 2] + a.w * wf[4 * i4 + 3];
;                 xb += b.x * wb[4 * i4] + b.y * wb[4 * i4 + 1] + b.z * wb[4 * i4 + 2] + b.w * wb[4 * i4 + 3]; }
;             lf[pp] = logsig2(xf) * (1.f / 16.f); lb[pp] = logsig2(xb) * (1.f / 16.f);
;         }
.LBB0_423:
	s_ashr_i32 s77, s76, 31
	s_lshr_b32 s78, s77, 27
	s_add_i32 s78, s76, s78
	s_ashr_i32 s78, s78, 5
	s_mul_i32 s80, s76, 0x10400
	v_readlane_b32 s88, v253, 48
	s_mul_hi_i32 s79, s76, 0x10400
	v_readlane_b32 s89, v253, 49
	s_add_u32 s88, s88, s80
	s_addc_u32 s89, s89, s79
	s_lshr_b32 s79, s78, 30
	s_add_i32 s79, s78, s79
	s_and_b32 s79, s79, 0x1fffffc
	s_sub_i32 s78, s78, s79
	v_lshl_or_b32 v2, s78, 7, v86
	v_bfe_u32 v3, v70, 5, 1
	v_lshlrev_b32_e32 v248, 2, v2
	v_lshl_add_u32 v2, v3, 14, v248
	v_add_u32_e32 v3, 0x1000, v2
	v_add_u32_e32 v4, 0x2000, v2
	v_add_u32_e32 v5, 0x3000, v2
	s_waitcnt lgkmcnt(0)
	s_waitcnt vmcnt(20)
	ds_write_b128 v107, v[34:37]
	s_waitcnt vmcnt(19)
	ds_write_b128 v108, v[38:41]
	s_waitcnt vmcnt(18)
	ds_write_b128 v109, v[42:45]
	s_waitcnt vmcnt(17)
	ds_write_b128 v110, v[46:49]
	s_waitcnt vmcnt(16)
	ds_write_b128 v111, v[50:53]
	s_waitcnt vmcnt(15)
	ds_write_b128 v112, v[54:57] offset:8192
	s_waitcnt vmcnt(14)
	ds_write_b128 v112, v[58:61] offset:25600
	s_waitcnt vmcnt(13)
	ds_write_b128 v113, v[62:65] offset:8192
	s_waitcnt vmcnt(12)
	ds_write_b128 v113, v[66:69] offset:25600
	global_load_dword v228, v2, s[12:13]
	global_load_dword v229, v2, s[12:13] offset:2048
	global_load_dword v230, v3, s[12:13]
	global_load_dword v231, v3, s[12:13] offset:2048
	global_load_dword v232, v4, s[12:13]
	global_load_dword v233, v4, s[12:13] offset:2048
	global_load_dword v234, v5, s[12:13]
	global_load_dword v235, v5, s[12:13] offset:2048
	global_load_dword v236, v2, s[16:17]
	global_load_dword v237, v2, s[16:17] offset:2048
	global_load_dword v238, v3, s[16:17]
	global_load_dword v239, v3, s[16:17] offset:2048
	global_load_dword v240, v4, s[16:17]
	global_load_dword v241, v4, s[16:17] offset:2048
	global_load_dword v242, v5, s[16:17]
	global_load_dword v243, v5, s[16:17] offset:2048
	global_load_dword v244, v248, s[14:15]
	global_load_dword v246, v248, s[18:19]
	s_waitcnt lgkmcnt(0)
	s_barrier
	ds_read_b128 v[212:215], v87
	ds_read_b128 v[216:219], v87 offset:16
	ds_read_b128 v[220:223], v87 offset:64
	ds_read_b128 v[224:227], v87 offset:80
	s_mov_b32 s100, 0xbfb8aa3b
	s_waitcnt vmcnt(10) lgkmcnt(2)
	v_mfma_f32_32x32x2_f32 v[180:195], v212, v228, 0
	v_mfma_f32_32x32x2_f32 v[180:195], v213, v229, v[180:195]
	v_mfma_f32_32x32x2_f32 v[180:195], v214, v230, v[180:195]
	v_mfma_f32_32x32x2_f32 v[180:195], v215, v231, v[180:195]
	v_mfma_f32_32x32x2_f32 v[180:195], v216, v232, v[180:195]
	v_mfma_f32_32x32x2_f32 v[180:195], v217, v233, v[180:195]
	v_mfma_f32_32x32x2_f32 v[180:195], v218, v234, v[180:195]
	v_mfma_f32_32x32x2_f32 v[180:195], v219, v235, v[180:195]
	s_waitcnt vmcnt(0) lgkmcnt(0)
	v_mfma_f32_32x32x2_f32 v[196:211], v220, v236, 0
	v_mfma_f32_32x32x2_f32 v[196:211], v221, v237, v[196:211]
	s_nop 15
	v_mfma_f32_32x32x2_f32 v[196:211], v222, v238, v[196:211]
	v_pk_add_f32 v[180:181], v[180:181], v[244:245] op_sel_hi:[1,0]
	v_pk_add_f32 v[182:183], v[182:183], v[244:245] op_sel_hi:[1,0]
	v_pk_add_f32 v[184:185], v[184:185], v[244:245] op_sel_hi:[1,0]
	v_pk_add_f32 v[186:187], v[186:187], v[244:245] op_sel_hi:[1,0]
	v_pk_add_f32 v[188:189], v[188:189], v[244:245] op_sel_hi:[1,0]
	v_pk_add_f32 v[190:191], v[190:191], v[244:245] op_sel_hi:[1,0]
	v_pk_add_f32 v[192:193], v[192:193], v[244:245] op_sel_hi:[1,0]
	v_pk_add_f32 v[194:195], v[194:195], v[244:245] op_sel_hi:[1,0]
	v_med3_f32 v180, v180, s66, v170
	v_med3_f32 v181, v181, s66, v170
	v_med3_f32 v182, v182, s66, v170
	v_mfma_f32_32x32x2_f32 v[196:211], v223, v239, v[196:211]
	v_med3_f32 v183, v183, s66, v170
	v_med3_f32 v184, v184, s66, v170
	v_med3_f32 v185, v185, s66, v170
	v_med3_f32 v186, v186, s66, v170
	v_med3_f32 v187, v187, s66, v170
	v_med3_f32 v188, v188, s66, v170
	v_med3_f32 v189, v189, s66, v170
	v_med3_f32 v190, v190, s66, v170
	v_med3_f32 v191, v191, s66, v170
	v_med3_f32 v192, v192, s66, v170
	v_med3_f32 v193, v193, s66, v170
	v_mfma_f32_32x32x2_f32 v[196:211], v224, v240, v[196:211]
	v_med3_f32 v194, v194, s66, v170
	v_med3_f32 v195, v195, s66, v170
	v_pk_mul_f32 v[180:181], v[180:181], s[100:101] op_sel_hi:[1,0]
	v_pk_mul_f32 v[182:183], v[182:183], s[100:101] op_sel_hi:[1,0]
	v_pk_mul_f32 v[184:185], v[184:185], s[100:101] op_sel_hi:[1,0]
	v_pk_mul_f32 v[186:187], v[186:187], s[100:101] op_sel_hi:[1,0]
	v_pk_mul_f32 v[188:189], v[188:189], s[100:101] op_sel_hi:[1,0]
	v_pk_mul_f32 v[190:191], v[190:191], s[100:101] op_sel_hi:[1,0]
	v_pk_mul_f32 v[192:193], v[192:193], s[100:101] op_sel_hi:[1,0]
	v_pk_mul_f32 v[194:195], v[194:195], s[100:101] op_sel_hi:[1,0]
	v_exp_f32_e32 v180, v180
	v_mfma_f32_32x32x2_f32 v[196:211], v225, v241, v[196:211]
	v_exp_f32_e32 v181, v181
	v_exp_f32_e32 v182, v182
	v_exp_f32_e32 v183, v183
	v_exp_f32_e32 v184, v184
	v_exp_f32_e32 v185, v185
	v_exp_f32_e32 v186, v186
	v_exp_f32_e32 v187, v187
	v_exp_f32_e32 v188, v188
	v_exp_f32_e32 v189, v189
	v_exp_f32_e32 v190, v190
	v_exp_f32_e32 v191, v191
	v_mfma_f32_32x32x2_f32 v[196:211], v226, v242, v[196:211]
	v_exp_f32_e32 v192, v192
	v_exp_f32_e32 v193, v193
	v_exp_f32_e32 v194, v194
	v_exp_f32_e32 v195, v195
	v_pk_add_f32 v[180:181], v[180:181], 1.0 op_sel_hi:[1,0]
	v_pk_add_f32 v[182:183], v[182:183], 1.0 op_sel_hi:[1,0]
	v_pk_add_f32 v[184:185], v[184:185], 1.0 op_sel_hi:[1,0]
	v_pk_add_f32 v[186:187], v[186:187], 1.0 op_sel_hi:[1,0]
	v_pk_add_f32 v[188:189], v[188:189], 1.0 op_sel_hi:[1,0]
	v_pk_add_f32 v[190:191], v[190:191], 1.0 op_sel_hi:[1,0]
	v_pk_add_f32 v[192:193], v[192:193], 1.0 op_sel_hi:[1,0]
	v_mfma_f32_32x32x2_f32 v[196:211], v227, v243, v[196:211]
; #define LAS __attribute__((address_space(3)))
; #define LBAR() do { asm volatile("s_waitcnt lgkmcnt(0)" ::: "memory"); __builtin_amdgcn_s_barrier(); asm volatile("" ::: "memory"); } while (0)
; __device__ __forceinline__ float logsig2(float x) { const float xc = fminf(fmaxf(x, -60.f), 60.f); return -__builtin_amdgcn_logf(1.0f + __builtin_amdgcn_exp2f(-1.4426950408889634f * xc)); }
; __device__ __forceinline__ void gla_prep_phase(LAS unsigned char* lds, const GlaPrepArgs& A, int bid, int G) {
;     ...
;         for (int pp = 0; pp < 16; ++pp) {
;             const LAS float* rr = (const LAS float*)(lds + L_R) + (pg * 16 + pp) * 32;
;             float xf = bf_, xb = bb_;
; #pragma unroll
;             for (int i4 = 0; i4 < 4; ++i4) { const f32x4 a = *(const LAS f32x4*)(rr + 4 * i4), b = *(const LAS f32x4*)(rr + 16 + 4 * i4);
;                 xf += a.x * wf[4 * i4] + a.y * wf[4 * i4 + 1] + a.z * wf[4 * i4 + 2] + a.w * wf[4 * i4 + 3];
;                 xb += b.x * wb[4 * i4] + b.y * wb[4 * i4 + 1] + b.z * wb[4 * i4 + 2] + b.w * wb[4 * i4 + 3]; }
;             lf[pp] = logsig2(xf) * (1.f / 16.f); lb[pp] = logsig2(xb) * (1.f / 16.f);
;         }
; #pragma unroll
;         for (int pp = 1; pp < 16; ++pp) lf[pp] += lf[pp - 1];
; #pragma unroll
;     ...
;         LAS float* tot = (LAS float*)(lds + L_TOT);
;         tot[pg * 128 + dd] = lf[15]; tot[512 + pg * 128 + dd] = lb[0];
;         LBAR();
;         float offf = 0.f, offb = 0.f, glf = 0.f, glb = 0.f;
; #pragma unroll
;         for (int g = 0; g < 4; ++g) { const float tf = tot[g * 128 + dd], tb = tot[512 + g * 128 + dd]; glf += tf; glb += tb; if (g < pg) offf += tf; if (g > pg) offb += tb; }
;         const float eglf = __builtin_amdgcn_exp2f(glf), eglb = __builtin_amdgcn_exp2f(glb);
;         if (pg == 0) { float* sc = (float*)(blob + B_SC); sc[dd] = eglf; sc[128 + dd] = eglb; }
	v_pk_add_f32 v[194:195], v[194:195], 1.0 op_sel_hi:[1,0]
	v_log_f32_e32 v180, v180
	v_log_f32_e32 v181, v181
	v_log_f32_e32 v182, v182
	v_log_f32_e32 v183, v183
	v_log_f32_e32 v184, v184
	v_log_f32_e32 v185, v185
	v_log_f32_e32 v186, v186
	v_log_f32_e32 v187, v187
	v_log_f32_e32 v188, v188
	v_log_f32_e32 v189, v189
	v_log_f32_e32 v190, v190
	v_log_f32_e32 v191, v191
	v_log_f32_e32 v192, v192
	v_log_f32_e32 v193, v193
	v_log_f32_e32 v194, v194
	v_log_f32_e32 v195, v195
	v_mul_f32_e32 v125, 0xbd800000, v180
	v_fmamk_f32 v159, v181, 0xbd800000, v125
	v_fmamk_f32 v126, v182, 0xbd800000, v159
	v_fmamk_f32 v96, v183, 0xbd800000, v126
	v_fmamk_f32 v32, v184, 0xbd800000, v96
	v_fmamk_f32 v30, v185, 0xbd800000, v32
	v_fmamk_f32 v28, v186, 0xbd800000, v30
	v_fmamk_f32 v26, v187, 0xbd800000, v28
	v_fmamk_f32 v24, v188, 0xbd800000, v26
	v_fmamk_f32 v22, v189, 0xbd800000, v24
	v_fmamk_f32 v20, v190, 0xbd800000, v22
	v_fmamk_f32 v18, v191, 0xbd800000, v20
	v_fmamk_f32 v16, v192, 0xbd800000, v18
	v_fmamk_f32 v14, v193, 0xbd800000, v16
	v_fmamk_f32 v12, v194, 0xbd800000, v14
	v_fmamk_f32 v11, v195, 0xbd800000, v12
	v_pk_add_f32 v[196:197], v[196:197], v[246:247] op_sel_hi:[1,0]
	v_pk_add_f32 v[198:199], v[198:199], v[246:247] op_sel_hi:[1,0]
	v_pk_add_f32 v[200:201], v[200:201], v[246:247] op_sel_hi:[1,0]
	v_pk_add_f32 v[202:203], v[202:203], v[246:247] op_sel_hi:[1,0]
	v_pk_add_f32 v[204:205], v[204:205], v[246:247] op_sel_hi:[1,0]
	v_pk_add_f32 v[206:207], v[206:207], v[246:247] op_sel_hi:[1,0]
	v_pk_add_f32 v[208:209], v[208:209], v[246:247] op_sel_hi:[1,0]
	v_pk_add_f32 v[210:211], v[210:211], v[246:247] op_sel_hi:[1,0]
	v_med3_f32 v196, v196, s66, v170
	v_med3_f32 v197, v197, s66, v170
	v_med3_f32 v198, v198, s66, v170
	v_med3_f32 v199, v199, s66, v170
	v_med3_f32 v200, v200, s66, v170
	v_med3_f32 v201, v201, s66, v170
	v_med3_f32 v202, v202, s66, v170
	v_med3_f32 v203, v203, s66, v170
	v_med3_f32 v204, v204, s66, v170
	v_med3_f32 v205, v205, s66, v170
	v_med3_f32 v206, v206, s66, v170
	v_med3_f32 v207, v207, s66, v170
	v_med3_f32 v208, v208, s66, v170
	v_med3_f32 v209, v209, s66, v170
	v_med3_f32 v210, v210, s66, v170
	v_med3_f32 v211, v211, s66, v170
	v_pk_mul_f32 v[196:197], v[196:197], s[100:101] op_sel_hi:[1,0]
	v_pk_mul_f32 v[198:199], v[198:199], s[100:101] op_sel_hi:[1,0]
	v_pk_mul_f32 v[200:201], v[200:201], s[100:101] op_sel_hi:[1,0]
	v_pk_mul_f32 v[202:203], v[202:203], s[100:101] op_sel_hi:[1,0]
	v_pk_mul_f32 v[204:205], v[204:205], s[100:101] op_sel_hi:[1,0]
	v_pk_mul_f32 v[206:207], v[206:207], s[100:101] op_sel_hi:[1,0]
	v_pk_mul_f32 v[208:209], v[208:209], s[100:101] op_sel_hi:[1,0]
	v_pk_mul_f32 v[210:211], v[210:211], s[100:101] op_sel_hi:[1,0]
	v_exp_f32_e32 v196, v196
	v_exp_f32_e32 v197, v197
	v_exp_f32_e32 v198, v198
	v_exp_f32_e32 v199, v199
	v_exp_f32_e32 v200, v200
	v_exp_f32_e32 v201, v201
	v_exp_f32_e32 v202, v202
	v_exp_f32_e32 v203, v203
	v_exp_f32_e32 v204, v204
	v_exp_f32_e32 v205, v205
	v_exp_f32_e32 v206, v206
	v_exp_f32_e32 v207, v207
	v_exp_f32_e32 v208, v208
	v_exp_f32_e32 v209, v209
	v_exp_f32_e32 v210, v210
	v_exp_f32_e32 v211, v211
	v_pk_add_f32 v[196:197], v[196:197], 1.0 op_sel_hi:[1,0]
	v_pk_add_f32 v[198:199], v[198:199], 1.0 op_sel_hi:[1,0]
	v_pk_add_f32 v[200:201], v[200:201], 1.0 op_sel_hi:[1,0]
	v_pk_add_f32 v[202:203], v[202:203], 1.0 op_sel_hi:[1,0]
	v_pk_add_f32 v[204:205], v[204:205], 1.0 op_sel_hi:[1,0]
	v_pk_add_f32 v[206:207], v[206:207], 1.0 op_sel_hi:[1,0]
	v_pk_add_f32 v[208:209], v[208:209], 1.0 op_sel_hi:[1,0]
	v_pk_add_f32 v[210:211], v[210:211], 1.0 op_sel_hi:[1,0]
	v_log_f32_e32 v211, v211
	v_log_f32_e32 v210, v210
	v_log_f32_e32 v209, v209
	v_log_f32_e32 v208, v208
	v_log_f32_e32 v207, v207
	v_log_f32_e32 v206, v206
	v_log_f32_e32 v205, v205
	v_log_f32_e32 v204, v204
	v_log_f32_e32 v203, v203
	v_log_f32_e32 v202, v202
	v_log_f32_e32 v201, v201
	v_log_f32_e32 v200, v200
	v_log_f32_e32 v199, v199
	v_log_f32_e32 v198, v198
	v_log_f32_e32 v197, v197
	v_log_f32_e32 v196, v196
	v_mul_f32_e32 v10, 0xbd800000, v211
	v_fmamk_f32 v13, v210, 0xbd800000, v10
	v_fmamk_f32 v15, v209, 0xbd800000, v13
	v_fmamk_f32 v17, v208, 0xbd800000, v15
	v_fmamk_f32 v19, v207, 0xbd800000, v17
	v_fmamk_f32 v21, v206, 0xbd800000, v19
	v_fmamk_f32 v23, v205, 0xbd800000, v21
	v_fmamk_f32 v25, v204, 0xbd800000, v23
	v_fmamk_f32 v27, v203, 0xbd800000, v25
	v_fmamk_f32 v29, v202, 0xbd800000, v27
	v_fmamk_f32 v31, v201, 0xbd800000, v29
	v_fmamk_f32 v33, v200, 0xbd800000, v31
	v_fmamk_f32 v97, v199, 0xbd800000, v33
	v_fmamk_f32 v128, v198, 0xbd800000, v97
	v_fmamk_f32 v127, v197, 0xbd800000, v128
	v_fmamk_f32 v129, v196, 0xbd800000, v127
	ds_write_b32 v98, v11
	ds_write_b32 v100, v129 offset:2048
	s_waitcnt lgkmcnt(0)
	s_barrier
	ds_read2st64_b32 v[4:5], v99 offset1:2
	ds_read2st64_b32 v[2:3], v99 offset0:8 offset1:10
	ds_read2st64_b32 v[8:9], v99 offset0:4 offset1:6
	ds_read2st64_b32 v[6:7], v99 offset0:12 offset1:14
	s_waitcnt lgkmcnt(3)
	v_add_f32_e32 v136, 0, v4
	s_waitcnt lgkmcnt(2)
	v_add_f32_e32 v137, 0, v2
	v_add_f32_e32 v2, v136, v5
	v_add_f32_e32 v4, v137, v3
	s_waitcnt lgkmcnt(1)
	v_add_f32_e32 v2, v2, v8
	s_waitcnt lgkmcnt(0)
	v_add_f32_e32 v4, v4, v6
	v_add_f32_e32 v2, v2, v9
	v_add_f32_e32 v138, v4, v7
	v_exp_f32_e32 v4, v2
	v_exp_f32_e32 v2, v138
	s_and_saveexec_b64 s[78:79], s[36:37]
	s_cbranch_execz .LBB0_425
	s_add_u32 s80, s88, 0x8000
	s_addc_u32 s81, s89, 0
	v_lshlrev_b32_e32 v140, 2, v86
	global_store_dword v140, v4, s[80:81]
	global_store_dword v140, v2, s[80:81] offset:512
